# MLA: one static s_setprio 1 for waves 4-7 for the whole phase (younger wave of each SIMD pair), on the reduced-VALU MLA loop
# speedup vs baseline: 1.0069x; 1.0069x over previous
; #define LAS __attribute__((address_space(3)))
; template <bool MLA> __device__ __forceinline__ void attn_unit(const AttnP& P, int b, int hh, int qb, LAS char* lds) {
;     ...
;     const int tid = threadIdx.x, wid = __builtin_amdgcn_readfirstlane(tid >> 6), lane = tid & 63, r32 = lane & 31, hi = lane >> 5;
;     LAS char* V_lds = lds; LAS char* K_lds = lds + 2 * VBYTES;
;     LAS float* ws = (LAS float*)(lds + 2 * VBYTES + 2 * KBYTES) + wid * 64; LAS float* li_l = ws; LAS float* al_l = ws + 32;
;     LAS float* bias_l = (LAS float*)(lds + 2 * VBYTES + 2 * KBYTES + 2048);
;     const int q0 = qb * 256; const size_t rowbase = (size_t)b * SEQ;
;     const int jt0 = MLA ? 0 : (q0 == 0 ? 0 : -2);
;     const int NT = MLA ? 4 * qb + 4 : 4 - jt0;
;     const int kbase0 = MLA ? 0 : q0 + 64 * jt0;
;     const int qlo = q0 + wid * 32, qm = qlo + r32 - 4 * hi;
;     ...
;         Kg = P.KN + rowbase * 2048 + hh * 128; Vg = P.V + rowbase * 2048 + hh * 128; Rg = P.KR + rowbase * 64;
;         { const int rA = 4 * wid + (lane >> 4), rB = rA + 32, cp = lane & 15; okA = (unsigned)(rA * 2048 + ((cp ^ (rA & 7)) << 3)); okB = (unsigned)(rB * 2048 + ((cp ^ (rB & 7)) << 3)); }
;         { const int rr = 8 * wid + (lane >> 3), cp = lane & 7; orp = (unsigned)(rr * 64 + ((cp ^ (rr & 7)) << 3)); }
;         { const int stA = 2 * wid + (lane >> 5), stB = stA + 16; const int kl = (lane & 31) >> 2, c8 = 8 * (lane & 3);
;           const int kkA = (stA >> 2) * 8 + kl, kkB = (stB >> 2) * 8 + kl;
;           const int kA = (kkA & ~0xC) | ((kkA & 4) << 1) | ((kkA & 8) >> 1), kB = (kkB & ~0xC) | ((kkB & 4) << 1) | ((kkB & 8) >> 1);
;           ovA = (unsigned)(kA * 2048 + 32 * (stA & 3) + c8); ovB = (unsigned)(kB * 2048 + 32 * (stB & 3) + c8); }
;     } else { Kg = P.KS + (rowbase + sr8) * 256 + (hh >> 3) * 64 + ch8 * 8; Vg = P.VS + (rowbase + sr8) * 256 + (hh >> 3) * 64 + ch8 * 8; }
;     const int kws = KSWZ64(sr8, ch8), vst0 = v_st<NCB>(sr8, ch8 * 8);
; __global__ void __launch_bounds__(512) fwd_mega(Args a) {
;     ...
;     if (IN(3)) {
;         att::AttnP P{QN, QR, KN, KR, VV, QS, KS, VS, a.sinks, a.rel};
;     ...
;         for (int it = vcu; it < 1024; it += G) { const int bh = it >> 5, s = it & 31;
;             att::attn_unit<true>(P, bh >> 4, bh & 15, 63 - s, (LAS char*)lds);
.LBB0_301:
	s_cmp_lt_i32 s54, 4
	s_cselect_b64 s[4:5], -1, 0
	s_and_b64 s[44:45], s[4:5], s[0:1]
	s_andn2_b64 vcc, exec, s[44:45]
	s_cbranch_vccnz .LBB0_682
	s_cmpk_gt_i32 s2, 0x3ff
	v_lshrrev_b32_e32 v1, 5, v206
	v_and_b32_e32 v198, 7, v162
	v_lshrrev_b32_e32 v200, 2, v162
	v_lshlrev_b32_e32 v147, 3, v162
	v_lshlrev_b32_e32 v199, 1, v162
	v_cmp_gt_u32_e64 s[0:1], 32, v206
	v_and_b32_e32 v151, 1, v162
	s_cbranch_scc1 .LBB0_597
	v_readfirstlane_b32 s4, v162
	s_nop 3
	s_lshr_b32 s4, s4, 6
	s_lshl_b32 s5, s4, 10
	s_add_u32 s6, s52, 0x1e000000
	s_addc_u32 s7, s53, 0
	s_add_u32 s8, s52, 0x26000000
	s_addc_u32 s9, s53, 0
	s_add_u32 s12, s52, 0x2a000000
	s_addc_u32 s13, s53, 0
	s_add_u32 s14, s52, 0x13c00000
	s_addc_u32 s15, s53, 0
	s_add_u32 s16, s52, 0x32000000
	s_addc_u32 s17, s53, 0
	s_mov_b32 s72, 0x4138aa3b
	v_mov_b32_e32 v245, 0xff800000
	v_mov_b32_e32 v248, 0
	v_and_b32_e32 v221, 15, v206
	v_lshrrev_b32_e32 v222, 4, v206
	v_lshrrev_b32_e32 v223, 1, v221
	v_xor_b32_e32 v223, v223, v222
	v_lshlrev_b32_e32 v223, 4, v223
	v_lshl_or_b32 v224, v221, 7, v223
	v_xor_b32_e32 v225, 64, v224
	v_lshrrev_b32_e32 v223, 1, v222
	v_lshlrev_b32_e32 v223, 11, v223
	v_and_b32_e32 v220, 1, v222
	v_lshl_or_b32 v223, v220, 8, v223
	v_lshrrev_b32_e32 v226, 2, v221
	v_lshl_or_b32 v223, v226, 6, v223
	v_and_b32_e32 v226, 3, v221
	v_lshl_or_b32 v223, v226, 3, v223
	v_lshlrev_b32_e32 v220, 5, v220
	v_or_b32_e32 v226, v223, v220
	v_xor_b32_e32 v220, 32, v220
	v_or_b32_e32 v227, v223, v220
	v_add_u32_e32 v224, 0x8000, v224
	v_add_u32_e32 v228, 0x6000, v224
	v_add_u32_e32 v230, 0x4000, v226
	v_add_u32_e32 v225, 0x8000, v225
	v_add_u32_e32 v229, 0x6000, v225
	v_add_u32_e32 v231, 0x4000, v227
	v_lshlrev_b32_e32 v223, 2, v222
	v_sub_u32_e32 v243, v221, v223
	v_xor_b32_e32 v246, 16, v206
	v_lshlrev_b32_e32 v246, 2, v246
	v_xor_b32_e32 v247, 32, v206
	v_lshlrev_b32_e32 v247, 2, v247
	v_lshlrev_b32_e32 v223, 4, v222
	v_lshl_or_b32 v237, v221, 12, v223
	v_add_u32_e32 v238, 0x10000, v237
	v_lshl_or_b32 v239, v221, 11, v223
	v_add_u32_e32 v240, 0x8000, v239
	v_lshlrev_b32_e32 v223, 3, v222
	v_lshl_or_b32 v241, v221, 12, v223
	v_add_u32_e32 v242, 0x10000, v241
	v_bfe_u32 v221, v162, 4, 3
	v_bitop3_b32 v221, v221, v162, 7 bitop3:0x78
	v_lshlrev_b32_e32 v221, 4, v221
	v_lshrrev_b32_e32 v222, 3, v162
	v_lshl_or_b32 v232, v222, 12, v221
	v_add_u32_e32 v233, 0x80, v232
	v_lshl_or_b32 v234, v222, 7, v221
	v_bfe_u32 v221, v206, 2, 3
	v_lshrrev_b32_e32 v222, 2, v221
	v_lshlrev_b32_e32 v222, 1, v222
	v_and_b32_e32 v223, 3, v206
	v_xor_b32_e32 v223, v223, v222
	v_lshlrev_b32_e32 v223, 4, v223
	v_lshrrev_b32_e32 v222, 5, v206
	v_lshl_or_b32 v223, v222, 6, v223
	s_lshr_b32 s36, s4, 1
	s_lshl_b32 s36, s36, 15
	s_and_b32 s37, s4, 1
	s_lshl_b32 s37, s37, 7
	s_add_i32 s36, s36, s37
	v_lshl_or_b32 v223, v221, 12, v223
	v_add_u32_e32 v235, s36, v223
	v_add_u32_e32 v236, 0x20000, v235
	s_cmp_ge_u32 s4, 4
	s_cbranch_scc0 .Lm16_noprio
	s_setprio 1
.Lm16_noprio:
	s_mov_b32 s28, s2

; #define LAS __attribute__((address_space(3)))
; __device__ __forceinline__ int crow(int r, int hi) { return (r & 3) + 8 * (r >> 2) + 4 * hi; }
; __device__ __forceinline__ unsigned cvtpk(float lo, float hi) { f32x2_cv v = {lo, hi}; bf16x2_cv b = __builtin_convertvector(v, bf16x2_cv); return __builtin_bit_cast(unsigned, b); }
; template <bool MLA> __device__ __forceinline__ void attn_unit(const AttnP& P, int b, int hh, int qb, LAS char* lds) {
;     ...
;     if (hi == 0) li_l[r32] = l_reg; asm volatile("s_waitcnt lgkmcnt(0)" ::: "memory");
;     bf16_t* Ow = (MLA ? P.QN + (rowbase + qlo) * 2048 + hh * 128 : P.QS + (rowbase + qlo) * 2048 + hh * 64);
; #pragma unroll
;     for (int r = 0; r < 16; ++r) { const int orow = crow(r, hi); const float rl = __builtin_amdgcn_rcpf(li_l[orow]);
; #pragma unroll
;         for (int d0 = 0; d0 < NCB; ++d0) { const float v = o[d0][r] * rl; const float vn = __shfl_xor(v, 1);
;             if ((r32 & 1) == 0) *(unsigned*)(Ow + (size_t)orow * 2048 + d0 * 32 + r32) = cvtpk(v, vn); } }
; __global__ void __launch_bounds__(512) fwd_mega(Args a) {
;     ...
;         for (int it = vcu; it < 1024; it += G) { const int bh = it >> 5, s = it & 31;
;             att::attn_unit<true>(P, bh >> 4, bh & 15, 63 - s, (LAS char*)lds);
;             att::attn_unit<true>(P, bh >> 4, bh & 15, s, (LAS char*)lds); }
.Lm16_done:
	s_nop 7
	v_rcp_f32_e32 v216, v146
	v_rcp_f32_e32 v217, v150
	s_nop 0
	v_mul_f32_e32 v2, v2, v216
	v_mul_f32_e32 v3, v3, v216
	v_mul_f32_e32 v4, v4, v216
	v_mul_f32_e32 v5, v5, v216
	v_cvt_pk_bf16_f32 v2, v2, v3
	v_cvt_pk_bf16_f32 v3, v4, v5
	global_store_dwordx2 v241, v[2:3], s[66:67] offset:0
	v_mul_f32_e32 v6, v6, v217
	v_mul_f32_e32 v7, v7, v217
	v_mul_f32_e32 v8, v8, v217
	v_mul_f32_e32 v9, v9, v217
	v_cvt_pk_bf16_f32 v6, v6, v7
	v_cvt_pk_bf16_f32 v7, v8, v9
	global_store_dwordx2 v242, v[6:7], s[66:67] offset:0
	v_mul_f32_e32 v10, v10, v216
	v_mul_f32_e32 v11, v11, v216
	v_mul_f32_e32 v12, v12, v216
	v_mul_f32_e32 v13, v13, v216
	v_cvt_pk_bf16_f32 v10, v10, v11
	v_cvt_pk_bf16_f32 v11, v12, v13
	global_store_dwordx2 v241, v[10:11], s[66:67] offset:32
	v_mul_f32_e32 v14, v14, v217
	v_mul_f32_e32 v15, v15, v217
	v_mul_f32_e32 v16, v16, v217
	v_mul_f32_e32 v17, v17, v217
	v_cvt_pk_bf16_f32 v14, v14, v15
	v_cvt_pk_bf16_f32 v15, v16, v17
	global_store_dwordx2 v242, v[14:15], s[66:67] offset:32
	v_mul_f32_e32 v18, v18, v216
	v_mul_f32_e32 v19, v19, v216
	v_mul_f32_e32 v20, v20, v216
	v_mul_f32_e32 v21, v21, v216
	v_cvt_pk_bf16_f32 v18, v18, v19
	v_cvt_pk_bf16_f32 v19, v20, v21
	global_store_dwordx2 v241, v[18:19], s[66:67] offset:64
	v_mul_f32_e32 v22, v22, v217
	v_mul_f32_e32 v23, v23, v217
	v_mul_f32_e32 v24, v24, v217
	v_mul_f32_e32 v25, v25, v217
	v_cvt_pk_bf16_f32 v22, v22, v23
	v_cvt_pk_bf16_f32 v23, v24, v25
	global_store_dwordx2 v242, v[22:23], s[66:67] offset:64
	v_mul_f32_e32 v26, v26, v216
	v_mul_f32_e32 v27, v27, v216
	v_mul_f32_e32 v28, v28, v216
	v_mul_f32_e32 v29, v29, v216
	v_cvt_pk_bf16_f32 v26, v26, v27
	v_cvt_pk_bf16_f32 v27, v28, v29
	global_store_dwordx2 v241, v[26:27], s[66:67] offset:96
	v_mul_f32_e32 v30, v30, v217
	v_mul_f32_e32 v31, v31, v217
	v_mul_f32_e32 v32, v32, v217
	v_mul_f32_e32 v33, v33, v217
	v_cvt_pk_bf16_f32 v30, v30, v31
	v_cvt_pk_bf16_f32 v31, v32, v33
	global_store_dwordx2 v242, v[30:31], s[66:67] offset:96
	v_mul_f32_e32 v34, v34, v216
	v_mul_f32_e32 v35, v35, v216
	v_mul_f32_e32 v36, v36, v216
	v_mul_f32_e32 v37, v37, v216
	v_cvt_pk_bf16_f32 v34, v34, v35
	v_cvt_pk_bf16_f32 v35, v36, v37
	global_store_dwordx2 v241, v[34:35], s[66:67] offset:128
	v_mul_f32_e32 v38, v38, v217
	v_mul_f32_e32 v39, v39, v217
	v_mul_f32_e32 v40, v40, v217
	v_mul_f32_e32 v41, v41, v217
	v_cvt_pk_bf16_f32 v38, v38, v39
	v_cvt_pk_bf16_f32 v39, v40, v41
	global_store_dwordx2 v242, v[38:39], s[66:67] offset:128
	v_mul_f32_e32 v42, v42, v216
	v_mul_f32_e32 v43, v43, v216
	v_mul_f32_e32 v44, v44, v216
	v_mul_f32_e32 v45, v45, v216
	v_cvt_pk_bf16_f32 v42, v42, v43
	v_cvt_pk_bf16_f32 v43, v44, v45
	global_store_dwordx2 v241, v[42:43], s[66:67] offset:160
	v_mul_f32_e32 v46, v46, v217
	v_mul_f32_e32 v47, v47, v217
	v_mul_f32_e32 v48, v48, v217
	v_mul_f32_e32 v49, v49, v217
	v_cvt_pk_bf16_f32 v46, v46, v47
	v_cvt_pk_bf16_f32 v47, v48, v49
	global_store_dwordx2 v242, v[46:47], s[66:67] offset:160
	v_mul_f32_e32 v50, v50, v216
	v_mul_f32_e32 v51, v51, v216
	v_mul_f32_e32 v52, v52, v216
	v_mul_f32_e32 v53, v53, v216
	v_cvt_pk_bf16_f32 v50, v50, v51
	v_cvt_pk_bf16_f32 v51, v52, v53
	global_store_dwordx2 v241, v[50:51], s[66:67] offset:192
	v_mul_f32_e32 v54, v54, v217
	v_mul_f32_e32 v55, v55, v217
	v_mul_f32_e32 v56, v56, v217
	v_mul_f32_e32 v57, v57, v217
	v_cvt_pk_bf16_f32 v54, v54, v55
	v_cvt_pk_bf16_f32 v55, v56, v57
	global_store_dwordx2 v242, v[54:55], s[66:67] offset:192
	v_mul_f32_e32 v58, v58, v216
	v_mul_f32_e32 v59, v59, v216
	v_mul_f32_e32 v60, v60, v216
	v_mul_f32_e32 v61, v61, v216
	v_cvt_pk_bf16_f32 v58, v58, v59
	v_cvt_pk_bf16_f32 v59, v60, v61
	global_store_dwordx2 v241, v[58:59], s[66:67] offset:224
	v_mul_f32_e32 v62, v62, v217
	v_mul_f32_e32 v63, v63, v217
	v_mul_f32_e32 v64, v64, v217
	v_mul_f32_e32 v65, v65, v217
	v_cvt_pk_bf16_f32 v62, v62, v63
	v_cvt_pk_bf16_f32 v63, v64, v65
	global_store_dwordx2 v242, v[62:63], s[66:67] offset:224
	s_add_u32 s29, s29, 1
	s_cmp_lt_u32 s29, 2
	s_cbranch_scc1 .Lm16_unit
	s_add_u32 s28, s28, s3
	s_cmp_lt_u32 s28, 0x400
	s_cbranch_scc1 .Lm16_item
	s_waitcnt vmcnt(0) lgkmcnt(0)
	s_setprio 0
